# adds batched sample-block K loads, deeper win-copy loads and the ring-prefetched down skinny item on top of the LN signal version
# speedup vs baseline: 1.0098x; 1.0079x over previous
.LBB0_745:
	v_add_u32_e32 v9, 64, v8
	v_cmp_gt_i32_e64 s[4:5], 0, v9
	global_load_dwordx4 v[20:23], v[4:5], off nt
	v_lshl_add_u64 v[4:5], v[4:5], 0, s[62:63]
	global_load_dwordx4 v[24:27], v[4:5], off nt
	v_lshl_add_u64 v[4:5], v[4:5], 0, s[62:63]
	global_load_dwordx4 v[28:31], v[4:5], off nt
	v_lshl_add_u64 v[4:5], v[4:5], 0, s[62:63]
	global_load_dwordx4 v[32:35], v[4:5], off nt
	v_lshl_add_u64 v[4:5], v[4:5], 0, s[62:63]
	global_load_dwordx4 v[36:39], v[4:5], off nt
	v_lshl_add_u64 v[4:5], v[4:5], 0, s[62:63]
	global_load_dwordx4 v[40:43], v[4:5], off nt
	v_lshl_add_u64 v[4:5], v[4:5], 0, s[62:63]
	global_load_dwordx4 v[44:47], v[4:5], off nt
	v_lshl_add_u64 v[4:5], v[4:5], 0, s[62:63]
	global_load_dwordx4 v[48:51], v[4:5], off nt
	v_lshl_add_u64 v[4:5], v[4:5], 0, s[62:63]
	global_load_dwordx4 v[52:55], v[4:5], off nt
	v_lshl_add_u64 v[4:5], v[4:5], 0, s[62:63]
	global_load_dwordx4 v[56:59], v[4:5], off nt
	v_lshl_add_u64 v[4:5], v[4:5], 0, s[62:63]
	global_load_dwordx4 v[60:63], v[4:5], off nt
	v_lshl_add_u64 v[4:5], v[4:5], 0, s[62:63]
	global_load_dwordx4 v[64:67], v[4:5], off nt
	v_lshl_add_u64 v[4:5], v[4:5], 0, s[62:63]
	global_load_dwordx4 v[68:71], v[4:5], off nt
	v_lshl_add_u64 v[4:5], v[4:5], 0, s[62:63]
	global_load_dwordx4 v[72:75], v[4:5], off nt
	v_lshl_add_u64 v[4:5], v[4:5], 0, s[62:63]
	global_load_dwordx4 v[76:79], v[4:5], off nt
	v_lshl_add_u64 v[4:5], v[4:5], 0, s[62:63]
	s_and_saveexec_b64 s[8:9], s[4:5]
	global_load_dwordx4 v[10:13], v[4:5], off nt
	s_mov_b64 exec, s[8:9]
	s_waitcnt vmcnt(8)
	global_store_dwordx4 v[6:7], v[20:23], off nt
	v_lshl_add_u64 v[6:7], v[6:7], 0, s[62:63]
	global_store_dwordx4 v[6:7], v[24:27], off nt
	v_lshl_add_u64 v[6:7], v[6:7], 0, s[62:63]
	global_store_dwordx4 v[6:7], v[28:31], off nt
	v_lshl_add_u64 v[6:7], v[6:7], 0, s[62:63]
	global_store_dwordx4 v[6:7], v[32:35], off nt
	v_lshl_add_u64 v[6:7], v[6:7], 0, s[62:63]
	global_store_dwordx4 v[6:7], v[36:39], off nt
	v_lshl_add_u64 v[6:7], v[6:7], 0, s[62:63]
	global_store_dwordx4 v[6:7], v[40:43], off nt
	v_lshl_add_u64 v[6:7], v[6:7], 0, s[62:63]
	global_store_dwordx4 v[6:7], v[44:47], off nt
	v_lshl_add_u64 v[6:7], v[6:7], 0, s[62:63]
	global_store_dwordx4 v[6:7], v[48:51], off nt
	v_lshl_add_u64 v[6:7], v[6:7], 0, s[62:63]
	s_waitcnt vmcnt(8)
	global_store_dwordx4 v[6:7], v[52:55], off nt
	v_lshl_add_u64 v[6:7], v[6:7], 0, s[62:63]
	global_store_dwordx4 v[6:7], v[56:59], off nt
	v_lshl_add_u64 v[6:7], v[6:7], 0, s[62:63]
	global_store_dwordx4 v[6:7], v[60:63], off nt
	v_lshl_add_u64 v[6:7], v[6:7], 0, s[62:63]
	global_store_dwordx4 v[6:7], v[64:67], off nt
	v_lshl_add_u64 v[6:7], v[6:7], 0, s[62:63]
	global_store_dwordx4 v[6:7], v[68:71], off nt
	v_lshl_add_u64 v[6:7], v[6:7], 0, s[62:63]
	global_store_dwordx4 v[6:7], v[72:75], off nt
	v_lshl_add_u64 v[6:7], v[6:7], 0, s[62:63]
	global_store_dwordx4 v[6:7], v[76:79], off nt
	v_lshl_add_u64 v[6:7], v[6:7], 0, s[62:63]
	s_and_saveexec_b64 s[8:9], s[4:5]
	global_store_dwordx4 v[6:7], v[10:13], off nt
	s_mov_b64 exec, s[8:9]
	s_branch .LBB0_742

.LBB0_1465:
	s_lshl_b32 s16, s87, 2
	s_add_u32 s14, s14, s16
	v_cmp_gt_u32_e32 vcc, s46, v174
	s_addc_u32 s15, s15, 0
	v_lshl_add_u64 v[18:19], v[162:163], 2, s[14:15]
	v_cndmask_b32_e32 v0, 0, v165, vcc
	v_lshlrev_b32_e32 v16, 2, v0
	v_lshl_add_u64 v[10:11], v[18:19], 0, v[16:17]
	v_cmp_gt_i32_e64 s[16:17], s46, v190
	v_cmp_gt_i32_e64 s[20:21], s46, v192
	v_cmp_gt_i32_e64 s[24:25], s46, v194
	v_cmp_gt_i32_e64 s[28:29], s46, v196
	v_cmp_gt_i32_e64 s[34:35], s46, v198
	v_cmp_gt_i32_e64 s[38:39], s46, v200
	v_cmp_gt_i32_e64 s[42:43], s46, v202
	v_cndmask_b32_e64 v76, 0, v192, s[20:21]
	v_cndmask_b32_e64 v84, 0, v194, s[24:25]
	v_cndmask_b32_e64 v92, 0, v196, s[28:29]
	v_cndmask_b32_e64 v100, 0, v198, s[34:35]
	v_cndmask_b32_e64 v108, 0, v200, s[38:39]
	v_cndmask_b32_e64 v116, 0, v202, s[42:43]
	v_ashrrev_i32_e32 v77, 31, v76
	v_ashrrev_i32_e32 v85, 31, v84
	v_ashrrev_i32_e32 v93, 31, v92
	v_ashrrev_i32_e32 v101, 31, v100
	v_ashrrev_i32_e32 v109, 31, v108
	v_ashrrev_i32_e32 v117, 31, v116
	v_lshlrev_b64 v[76:77], 10, v[76:77]
	v_lshlrev_b64 v[84:85], 10, v[84:85]
	v_lshlrev_b64 v[92:93], 10, v[92:93]
	v_lshlrev_b64 v[100:101], 10, v[100:101]
	v_lshlrev_b64 v[108:109], 10, v[108:109]
	v_lshlrev_b64 v[116:117], 10, v[116:117]
	v_cmp_gt_i32_e64 s[18:19], s46, v191
	v_cmp_gt_i32_e64 s[22:23], s46, v193
	v_cmp_gt_i32_e64 s[26:27], s46, v195
	v_cmp_gt_i32_e64 s[30:31], s46, v197
	v_cmp_gt_i32_e64 s[36:37], s46, v199
	v_cmp_gt_i32_e64 s[40:41], s46, v201
	v_cmp_gt_i32_e64 s[44:45], s46, v203
	v_mov_b64_e32 v[120:121], v[10:11]
	v_cmp_gt_u32_e64 s[100:101], s46, v184
	v_mov_b32_e32 v123, 0
	v_mov_b32_e32 v125, 0
	v_mov_b32_e32 v127, 0
	v_cndmask_b32_e64 v122, 0, v185, s[100:101]
	v_cmp_gt_u32_e64 s[100:101], s46, v186
	v_lshlrev_b32_e32 v122, 2, v122
	v_lshl_add_u64 v[122:123], v[18:19], 0, v[122:123]
	v_cndmask_b32_e64 v124, 0, v187, s[100:101]
	v_cmp_gt_u32_e64 s[100:101], s46, v188
	v_lshlrev_b32_e32 v124, 2, v124
	v_lshl_add_u64 v[124:125], v[18:19], 0, v[124:125]
	v_cndmask_b32_e64 v126, 0, v189, s[100:101]
	v_lshlrev_b32_e32 v126, 2, v126
	v_lshl_add_u64 v[126:127], v[18:19], 0, v[126:127]
	global_load_dwordx4 v[0:3], v[120:121], off nt
	global_load_dwordx4 v[64:67], v[120:121], off offset:16 nt
	global_load_dwordx4 v[4:7], v[120:121], off offset:128 nt
	global_load_dwordx4 v[68:71], v[120:121], off offset:144 nt
	global_load_dwordx4 v[8:11], v[122:123], off nt
	global_load_dwordx4 v[72:75], v[122:123], off offset:16 nt
	global_load_dwordx4 v[12:15], v[122:123], off offset:128 nt
	global_load_dwordx4 v[80:83], v[122:123], off offset:144 nt
	global_load_dwordx4 v[60:63], v[124:125], off nt
	global_load_dwordx4 v[88:91], v[124:125], off offset:16 nt
	global_load_dwordx4 v[128:131], v[124:125], off offset:128 nt
	global_load_dwordx4 v[96:99], v[124:125], off offset:144 nt
	global_load_dwordx4 v[132:135], v[126:127], off nt
	global_load_dwordx4 v[104:107], v[126:127], off offset:16 nt
	global_load_dwordx4 v[136:139], v[126:127], off offset:128 nt
	global_load_dwordx4 v[112:115], v[126:127], off offset:144 nt
	s_waitcnt vmcnt(14)
	v_bfe_u32 v16, v0, 16, 1
	v_add3_u32 v16, v0, v16, s83
	v_bfe_u32 v250, v1, 16, 1
	v_lshrrev_b32_e32 v16, 16, v16
	v_add3_u32 v250, v1, v250, s83
	v_and_or_b32 v0, v250, s85, v16
	v_bfe_u32 v16, v2, 16, 1
	v_add3_u32 v16, v2, v16, s83
	v_bfe_u32 v250, v3, 16, 1
	v_lshrrev_b32_e32 v16, 16, v16
	v_add3_u32 v250, v3, v250, s83
	v_and_or_b32 v1, v250, s85, v16
	v_bfe_u32 v16, v64, 16, 1
	v_add3_u32 v16, v64, v16, s83
	v_bfe_u32 v250, v65, 16, 1
	v_lshrrev_b32_e32 v16, 16, v16
	v_add3_u32 v250, v65, v250, s83
	v_and_or_b32 v2, v250, s85, v16
	v_bfe_u32 v16, v66, 16, 1
	v_add3_u32 v16, v66, v16, s83
	v_bfe_u32 v250, v67, 16, 1
	v_lshrrev_b32_e32 v16, 16, v16
	v_add3_u32 v250, v67, v250, s83
	v_and_or_b32 v3, v250, s85, v16
	s_waitcnt vmcnt(12)
	v_bfe_u32 v16, v4, 16, 1
	v_add3_u32 v16, v4, v16, s83
	v_bfe_u32 v250, v5, 16, 1
	v_lshrrev_b32_e32 v16, 16, v16
	v_add3_u32 v250, v5, v250, s83
	v_and_or_b32 v4, v250, s85, v16
	v_bfe_u32 v16, v6, 16, 1
	v_add3_u32 v16, v6, v16, s83
	v_bfe_u32 v250, v7, 16, 1
	v_lshrrev_b32_e32 v16, 16, v16
	v_add3_u32 v250, v7, v250, s83
	v_and_or_b32 v5, v250, s85, v16
	v_bfe_u32 v16, v68, 16, 1
	v_add3_u32 v16, v68, v16, s83
	v_bfe_u32 v250, v69, 16, 1
	v_lshrrev_b32_e32 v16, 16, v16
	v_add3_u32 v250, v69, v250, s83
	v_and_or_b32 v6, v250, s85, v16
	v_bfe_u32 v16, v70, 16, 1
	v_add3_u32 v16, v70, v16, s83
	v_bfe_u32 v250, v71, 16, 1
	v_lshrrev_b32_e32 v16, 16, v16
	v_add3_u32 v250, v71, v250, s83
	v_and_or_b32 v7, v250, s85, v16
	s_waitcnt vmcnt(10)
	v_bfe_u32 v16, v8, 16, 1
	v_add3_u32 v16, v8, v16, s83
	v_bfe_u32 v250, v9, 16, 1
	v_lshrrev_b32_e32 v16, 16, v16
	v_add3_u32 v250, v9, v250, s83
	v_and_or_b32 v8, v250, s85, v16
	v_bfe_u32 v16, v10, 16, 1
	v_add3_u32 v16, v10, v16, s83
	v_bfe_u32 v250, v11, 16, 1
	v_lshrrev_b32_e32 v16, 16, v16
	v_add3_u32 v250, v11, v250, s83
	v_and_or_b32 v9, v250, s85, v16
	v_bfe_u32 v16, v72, 16, 1
	v_add3_u32 v16, v72, v16, s83
	v_bfe_u32 v250, v73, 16, 1
	v_lshrrev_b32_e32 v16, 16, v16
	v_add3_u32 v250, v73, v250, s83
	v_and_or_b32 v10, v250, s85, v16
	v_bfe_u32 v16, v74, 16, 1
	v_add3_u32 v16, v74, v16, s83
	v_bfe_u32 v250, v75, 16, 1
	v_lshrrev_b32_e32 v16, 16, v16
	v_add3_u32 v250, v75, v250, s83
	v_and_or_b32 v11, v250, s85, v16
	s_waitcnt vmcnt(8)
	v_bfe_u32 v16, v12, 16, 1
	v_add3_u32 v16, v12, v16, s83
	v_bfe_u32 v250, v13, 16, 1
	v_lshrrev_b32_e32 v16, 16, v16
	v_add3_u32 v250, v13, v250, s83
	v_and_or_b32 v12, v250, s85, v16
	v_bfe_u32 v16, v14, 16, 1
	v_add3_u32 v16, v14, v16, s83
	v_bfe_u32 v250, v15, 16, 1
	v_lshrrev_b32_e32 v16, 16, v16
	v_add3_u32 v250, v15, v250, s83
	v_and_or_b32 v13, v250, s85, v16
	v_bfe_u32 v16, v80, 16, 1
	v_add3_u32 v16, v80, v16, s83
	v_bfe_u32 v250, v81, 16, 1
	v_lshrrev_b32_e32 v16, 16, v16
	v_add3_u32 v250, v81, v250, s83
	v_and_or_b32 v14, v250, s85, v16
	v_bfe_u32 v16, v82, 16, 1
	v_add3_u32 v16, v82, v16, s83
	v_bfe_u32 v250, v83, 16, 1
	v_lshrrev_b32_e32 v16, 16, v16
	v_add3_u32 v250, v83, v250, s83
	v_and_or_b32 v15, v250, s85, v16
	s_waitcnt vmcnt(6)
	v_bfe_u32 v16, v60, 16, 1
	v_add3_u32 v16, v60, v16, s83
	v_bfe_u32 v250, v61, 16, 1
	v_lshrrev_b32_e32 v16, 16, v16
	v_add3_u32 v250, v61, v250, s83
	v_and_or_b32 v60, v250, s85, v16
	v_bfe_u32 v16, v62, 16, 1
	v_add3_u32 v16, v62, v16, s83
	v_bfe_u32 v250, v63, 16, 1
	v_lshrrev_b32_e32 v16, 16, v16
	v_add3_u32 v250, v63, v250, s83
	v_and_or_b32 v61, v250, s85, v16
	v_bfe_u32 v16, v88, 16, 1
	v_add3_u32 v16, v88, v16, s83
	v_bfe_u32 v250, v89, 16, 1
	v_lshrrev_b32_e32 v16, 16, v16
	v_add3_u32 v250, v89, v250, s83
	v_and_or_b32 v62, v250, s85, v16
	v_bfe_u32 v16, v90, 16, 1
	v_add3_u32 v16, v90, v16, s83
	v_bfe_u32 v250, v91, 16, 1
	v_lshrrev_b32_e32 v16, 16, v16
	v_add3_u32 v250, v91, v250, s83
	v_and_or_b32 v63, v250, s85, v16
	s_waitcnt vmcnt(4)
	v_bfe_u32 v16, v128, 16, 1
	v_add3_u32 v16, v128, v16, s83
	v_bfe_u32 v250, v129, 16, 1
	v_lshrrev_b32_e32 v16, 16, v16
	v_add3_u32 v250, v129, v250, s83
	v_and_or_b32 v128, v250, s85, v16
	v_bfe_u32 v16, v130, 16, 1
	v_add3_u32 v16, v130, v16, s83
	v_bfe_u32 v250, v131, 16, 1
	v_lshrrev_b32_e32 v16, 16, v16
	v_add3_u32 v250, v131, v250, s83
	v_and_or_b32 v129, v250, s85, v16
	v_bfe_u32 v16, v96, 16, 1
	v_add3_u32 v16, v96, v16, s83
	v_bfe_u32 v250, v97, 16, 1
	v_lshrrev_b32_e32 v16, 16, v16
	v_add3_u32 v250, v97, v250, s83
	v_and_or_b32 v130, v250, s85, v16
	v_bfe_u32 v16, v98, 16, 1
	v_add3_u32 v16, v98, v16, s83
	v_bfe_u32 v250, v99, 16, 1
	v_lshrrev_b32_e32 v16, 16, v16
	v_add3_u32 v250, v99, v250, s83
	v_and_or_b32 v131, v250, s85, v16
	s_waitcnt vmcnt(2)
	v_bfe_u32 v16, v132, 16, 1
	v_add3_u32 v16, v132, v16, s83
	v_bfe_u32 v250, v133, 16, 1
	v_lshrrev_b32_e32 v16, 16, v16
	v_add3_u32 v250, v133, v250, s83
	v_and_or_b32 v132, v250, s85, v16
	v_bfe_u32 v16, v134, 16, 1
	v_add3_u32 v16, v134, v16, s83
	v_bfe_u32 v250, v135, 16, 1
	v_lshrrev_b32_e32 v16, 16, v16
	v_add3_u32 v250, v135, v250, s83
	v_and_or_b32 v133, v250, s85, v16
	v_bfe_u32 v16, v104, 16, 1
	v_add3_u32 v16, v104, v16, s83
	v_bfe_u32 v250, v105, 16, 1
	v_lshrrev_b32_e32 v16, 16, v16
	v_add3_u32 v250, v105, v250, s83
	v_and_or_b32 v134, v250, s85, v16
	v_bfe_u32 v16, v106, 16, 1
	v_add3_u32 v16, v106, v16, s83
	v_bfe_u32 v250, v107, 16, 1
	v_lshrrev_b32_e32 v16, 16, v16
	v_add3_u32 v250, v107, v250, s83
	v_and_or_b32 v135, v250, s85, v16
	s_waitcnt vmcnt(0)
	v_bfe_u32 v16, v136, 16, 1
	v_add3_u32 v16, v136, v16, s83
	v_bfe_u32 v250, v137, 16, 1
	v_lshrrev_b32_e32 v16, 16, v16
	v_add3_u32 v250, v137, v250, s83
	v_and_or_b32 v136, v250, s85, v16
	v_bfe_u32 v16, v138, 16, 1
	v_add3_u32 v16, v138, v16, s83
	v_bfe_u32 v250, v139, 16, 1
	v_lshrrev_b32_e32 v16, 16, v16
	v_add3_u32 v250, v139, v250, s83
	v_and_or_b32 v137, v250, s85, v16
	v_bfe_u32 v16, v112, 16, 1
	v_add3_u32 v16, v112, v16, s83
	v_bfe_u32 v250, v113, 16, 1
	v_lshrrev_b32_e32 v16, 16, v16
	v_add3_u32 v250, v113, v250, s83
	v_and_or_b32 v138, v250, s85, v16
	v_bfe_u32 v16, v114, 16, 1
	v_add3_u32 v16, v114, v16, s83
	v_bfe_u32 v250, v115, 16, 1
	v_lshrrev_b32_e32 v16, 16, v16
	v_add3_u32 v250, v115, v250, s83
	v_and_or_b32 v139, v250, s85, v16
	s_nop 1
	v_mfma_f32_16x16x32_bf16 v[0:3], v[0:3], v[36:39], 0
	v_cndmask_b32_e64 v68, 0, v190, s[16:17]
	v_lshlrev_b32_e32 v16, 2, v166
	v_ashrrev_i32_e32 v69, 31, v68
	v_lshl_add_u64 v[18:19], s[14:15], 0, v[16:17]
	v_lshlrev_b64 v[68:69], 10, v[68:69]
	v_cmp_gt_i32_e64 s[14:15], s46, v172
	v_lshl_add_u64 v[68:69], v[18:19], 0, v[68:69]
	v_lshl_add_u64 v[76:77], v[18:19], 0, v[76:77]
	v_lshl_add_u64 v[84:85], v[18:19], 0, v[84:85]
	v_lshl_add_u64 v[92:93], v[18:19], 0, v[92:93]
	v_lshl_add_u64 v[100:101], v[18:19], 0, v[100:101]
	v_lshl_add_u64 v[108:109], v[18:19], 0, v[108:109]
	v_lshl_add_u64 v[116:117], v[18:19], 0, v[116:117]
	v_cmp_gt_i32_e64 s[46:47], s46, v204
	v_cndmask_b32_e64 v64, 0, v172, s[14:15]
	global_load_dwordx4 v[72:75], v[68:69], off offset:512 nt
	global_load_dwordx4 v[80:83], v[76:77], off offset:512 nt
	v_cndmask_b32_e64 v68, 0, v191, s[18:19]
	v_cndmask_b32_e64 v76, 0, v193, s[22:23]
	global_load_dwordx4 v[88:91], v[84:85], off offset:512 nt
	global_load_dwordx4 v[96:99], v[92:93], off offset:512 nt
	v_cndmask_b32_e64 v84, 0, v195, s[26:27]
	v_cndmask_b32_e64 v92, 0, v197, s[30:31]
	global_load_dwordx4 v[104:107], v[100:101], off offset:512 nt
	global_load_dwordx4 v[112:115], v[108:109], off offset:512 nt
	v_cndmask_b32_e64 v100, 0, v199, s[36:37]
	v_cndmask_b32_e64 v108, 0, v201, s[40:41]
	global_load_dwordx4 v[120:123], v[116:117], off offset:512 nt
	v_cndmask_b32_e64 v116, 0, v203, s[44:45]
	v_cndmask_b32_e64 v124, 0, v204, s[46:47]
	v_ashrrev_i32_e32 v65, 31, v64
	v_ashrrev_i32_e32 v69, 31, v68
	v_ashrrev_i32_e32 v77, 31, v76
	v_ashrrev_i32_e32 v85, 31, v84
	v_ashrrev_i32_e32 v93, 31, v92
	v_ashrrev_i32_e32 v101, 31, v100
	v_ashrrev_i32_e32 v109, 31, v108
	v_ashrrev_i32_e32 v117, 31, v116
	v_ashrrev_i32_e32 v125, 31, v124
	v_lshlrev_b64 v[64:65], 10, v[64:65]
	v_lshlrev_b64 v[68:69], 10, v[68:69]
	v_lshlrev_b64 v[76:77], 10, v[76:77]
	v_lshlrev_b64 v[84:85], 10, v[84:85]
	v_lshlrev_b64 v[92:93], 10, v[92:93]
	v_lshlrev_b64 v[100:101], 10, v[100:101]
	v_lshlrev_b64 v[108:109], 10, v[108:109]
	v_lshlrev_b64 v[116:117], 10, v[116:117]
	v_lshlrev_b64 v[124:125], 10, v[124:125]
	v_lshl_add_u64 v[64:65], v[18:19], 0, v[64:65]
	v_lshl_add_u64 v[68:69], v[18:19], 0, v[68:69]
	v_lshl_add_u64 v[76:77], v[18:19], 0, v[76:77]
	v_lshl_add_u64 v[84:85], v[18:19], 0, v[84:85]
	v_lshl_add_u64 v[92:93], v[18:19], 0, v[92:93]
	v_lshl_add_u64 v[100:101], v[18:19], 0, v[100:101]
	v_lshl_add_u64 v[108:109], v[18:19], 0, v[108:109]
	v_lshl_add_u64 v[116:117], v[18:19], 0, v[116:117]
	v_lshl_add_u64 v[18:19], v[18:19], 0, v[124:125]
	global_load_dwordx4 v[64:67], v[64:65], off offset:512 nt
	v_lshrrev_b32_e32 v16, s48, v140
	global_load_dwordx4 v[68:71], v[68:69], off offset:512 nt
	v_mfma_f32_16x16x32_bf16 v[140:143], v[4:7], v[40:43], v[0:3]
	global_load_dwordx4 v[76:79], v[76:77], off offset:512 nt
	v_and_b32_e32 v16, 1, v16
	global_load_dwordx4 v[84:87], v[84:85], off offset:512 nt
	v_mfma_f32_16x16x32_bf16 v[0:3], v[8:11], v[36:39], 0
	global_load_dwordx4 v[92:95], v[92:93], off offset:512 nt
	v_cmp_eq_u32_e32 vcc, 1, v16
	global_load_dwordx4 v[100:103], v[100:101], off offset:512 nt
	v_mfma_f32_16x16x32_bf16 v[144:147], v[12:15], v[40:43], v[0:3]
	global_load_dwordx4 v[108:111], v[108:109], off offset:512 nt
	v_cndmask_b32_e32 v16, -1, v151, vcc
	global_load_dwordx4 v[116:119], v[116:117], off offset:512 nt
	v_mfma_f32_16x16x32_bf16 v[0:3], v[60:63], v[36:39], 0
	global_load_dwordx4 v[124:127], v[18:19], off offset:512 nt
	v_cmp_gt_u32_e32 vcc, 63, v16
	v_mfma_f32_16x16x32_bf16 v[60:63], v[128:131], v[40:43], v[0:3]
	v_mfma_f32_16x16x32_bf16 v[0:3], v[132:135], v[36:39], 0
	v_mfma_f32_16x16x32_bf16 v[128:131], v[136:139], v[40:43], v[0:3]
	s_cbranch_vccz .LBB0_1467
	v_cmp_gt_i32_e32 vcc, v160, v16
	s_or_b64 vcc, s[6:7], vcc
	s_nop 3
	v_cndmask_b32_e32 v0, v140, v246, vcc
	v_cmp_ge_i32_e32 vcc, v160, v16
	s_or_b64 vcc, s[6:7], vcc
	s_nop 0
	v_cndmask_b32_e32 v1, v141, v246, vcc
	v_cmp_gt_i32_e32 vcc, v177, v16
	s_or_b64 vcc, s[6:7], vcc
	v_max3_f32 v4, v0, s96, v1
	v_cndmask_b32_e32 v2, v142, v246, vcc
	v_cmp_gt_i32_e32 vcc, v182, v16
	s_or_b64 vcc, s[6:7], vcc
	s_nop 0
	v_cndmask_b32_e32 v3, v143, v246, vcc
	v_cmp_gt_i32_e32 vcc, v205, v16
	s_or_b64 vcc, s[8:9], vcc
	v_max3_f32 v6, v4, v2, v3
	v_cndmask_b32_e32 v4, v144, v246, vcc
	v_cmp_gt_i32_e32 vcc, v206, v16
	s_or_b64 vcc, s[8:9], vcc
	s_nop 0
	v_cndmask_b32_e32 v5, v145, v246, vcc
	v_cmp_gt_i32_e32 vcc, v207, v16
	s_or_b64 vcc, s[8:9], vcc
	v_max3_f32 v8, v6, v4, v5
	v_cndmask_b32_e32 v6, v146, v246, vcc
	v_cmp_gt_i32_e32 vcc, v208, v16
	s_or_b64 vcc, s[8:9], vcc
	s_nop 0
	v_cndmask_b32_e32 v7, v147, v246, vcc
	v_cmp_gt_i32_e32 vcc, v209, v16
	s_or_b64 vcc, s[10:11], vcc
	v_max3_f32 v10, v8, v6, v7
	v_cndmask_b32_e32 v8, v60, v246, vcc
	v_cmp_gt_i32_e32 vcc, v210, v16
	s_or_b64 vcc, s[10:11], vcc
	s_nop 0
	v_cndmask_b32_e32 v9, v61, v246, vcc
	v_cmp_gt_i32_e32 vcc, v211, v16
	s_or_b64 vcc, s[10:11], vcc
	v_max3_f32 v12, v10, v8, v9
	v_cndmask_b32_e32 v10, v62, v246, vcc
	v_cmp_gt_i32_e32 vcc, v212, v16
	s_or_b64 vcc, s[10:11], vcc
	s_nop 0
	v_cndmask_b32_e32 v11, v63, v246, vcc
	v_cmp_gt_i32_e32 vcc, v213, v16
	s_or_b64 vcc, s[12:13], vcc
	v_max3_f32 v14, v12, v10, v11
	v_cndmask_b32_e32 v12, v128, v246, vcc
	v_cmp_gt_i32_e32 vcc, v214, v16
	s_or_b64 vcc, s[12:13], vcc
	s_nop 0
	v_cndmask_b32_e32 v13, v129, v246, vcc
	v_cmp_gt_i32_e32 vcc, v215, v16
	s_or_b64 vcc, s[12:13], vcc
	v_max3_f32 v18, v14, v12, v13
	v_cndmask_b32_e32 v14, v130, v246, vcc
	v_cmp_gt_i32_e32 vcc, v216, v16
	s_or_b64 vcc, s[12:13], vcc
	s_nop 0
	v_cndmask_b32_e32 v15, v131, v246, vcc
	v_max3_f32 v18, v18, v14, v15
	s_cbranch_execnz .LBB0_1458
	s_branch .LBB0_1457

.LBB0_1472:
	s_and_b32 s6, s51, 7
	s_cmp_lg_u32 s6, s33
	s_cbranch_scc1 .LBB0_1471
	s_cmpk_eq_i32 s46, 0xfe00
	s_cselect_b32 s38, 4, 64
	v_cmp_gt_u32_e32 vcc, s38, v174
	s_cselect_b32 s7, s45, s43
	s_cselect_b32 s6, s44, s42
	v_cndmask_b32_e32 v16, 0, v165, vcc
	v_lshl_add_u64 v[18:19], v[162:163], 2, s[6:7]
	v_lshlrev_b32_e32 v16, 2, v16
	v_lshl_add_u64 v[70:71], v[18:19], 0, v[16:17]
	v_cmp_gt_i32_e64 s[8:9], s38, v190
	v_cmp_gt_i32_e64 s[12:13], s38, v192
	v_cmp_gt_i32_e64 s[16:17], s38, v194
	v_cmp_gt_i32_e64 s[20:21], s38, v196
	v_cmp_gt_i32_e64 s[24:25], s38, v198
	v_cmp_gt_i32_e64 s[28:29], s38, v200
	v_cmp_gt_i32_e64 s[34:35], s38, v202
	v_cndmask_b32_e64 v92, 0, v192, s[12:13]
	v_cndmask_b32_e64 v100, 0, v194, s[16:17]
	v_cndmask_b32_e64 v108, 0, v196, s[20:21]
	v_cndmask_b32_e64 v116, 0, v198, s[24:25]
	v_cndmask_b32_e64 v124, 0, v200, s[28:29]
	v_cndmask_b32_e64 v132, 0, v202, s[34:35]
	v_ashrrev_i32_e32 v93, 31, v92
	v_ashrrev_i32_e32 v101, 31, v100
	v_ashrrev_i32_e32 v109, 31, v108
	v_ashrrev_i32_e32 v117, 31, v116
	v_ashrrev_i32_e32 v125, 31, v124
	v_ashrrev_i32_e32 v133, 31, v132
	v_lshlrev_b64 v[92:93], 10, v[92:93]
	v_lshlrev_b64 v[100:101], 10, v[100:101]
	v_lshlrev_b64 v[108:109], 10, v[108:109]
	v_lshlrev_b64 v[116:117], 10, v[116:117]
	v_lshlrev_b64 v[124:125], 10, v[124:125]
	v_lshlrev_b64 v[132:133], 10, v[132:133]
	v_cmp_gt_i32_e64 s[10:11], s38, v191
	v_cmp_gt_i32_e64 s[14:15], s38, v193
	v_cmp_gt_i32_e64 s[18:19], s38, v195
	v_cmp_gt_i32_e64 s[22:23], s38, v197
	v_cmp_gt_i32_e64 s[26:27], s38, v199
	v_cmp_gt_i32_e64 s[30:31], s38, v201
	v_cmp_gt_i32_e64 s[36:37], s38, v203
	v_mov_b64_e32 v[140:141], v[70:71]
	v_cmp_gt_u32_e64 s[100:101], s38, v184
	v_mov_b32_e32 v143, 0
	v_mov_b32_e32 v251, 0
	v_mov_b32_e32 v253, 0
	v_cndmask_b32_e64 v142, 0, v185, s[100:101]
	v_cmp_gt_u32_e64 s[100:101], s38, v186
	v_lshlrev_b32_e32 v142, 2, v142
	v_lshl_add_u64 v[142:143], v[18:19], 0, v[142:143]
	v_cndmask_b32_e64 v250, 0, v187, s[100:101]
	v_cmp_gt_u32_e64 s[100:101], s38, v188
	v_lshlrev_b32_e32 v250, 2, v250
	v_lshl_add_u64 v[250:251], v[18:19], 0, v[250:251]
	v_cndmask_b32_e64 v252, 0, v189, s[100:101]
	v_lshlrev_b32_e32 v252, 2, v252
	v_lshl_add_u64 v[252:253], v[18:19], 0, v[252:253]
	global_load_dwordx4 v[60:63], v[140:141], off nt
	global_load_dwordx4 v[80:83], v[140:141], off offset:16 nt
	global_load_dwordx4 v[64:67], v[140:141], off offset:128 nt
	global_load_dwordx4 v[88:91], v[140:141], off offset:144 nt
	global_load_dwordx4 v[68:71], v[142:143], off nt
	global_load_dwordx4 v[96:99], v[142:143], off offset:16 nt
	global_load_dwordx4 v[72:75], v[142:143], off offset:128 nt
	global_load_dwordx4 v[104:107], v[142:143], off offset:144 nt
	global_load_dwordx4 v[76:79], v[250:251], off nt
	global_load_dwordx4 v[112:115], v[250:251], off offset:16 nt
	global_load_dwordx4 v[144:147], v[250:251], off offset:128 nt
	global_load_dwordx4 v[120:123], v[250:251], off offset:144 nt
	global_load_dwordx4 v[148:151], v[252:253], off nt
	global_load_dwordx4 v[128:131], v[252:253], off offset:16 nt
	global_load_dwordx4 v[152:155], v[252:253], off offset:128 nt
	global_load_dwordx4 v[136:139], v[252:253], off offset:144 nt
	s_waitcnt vmcnt(14)
	v_bfe_u32 v16, v60, 16, 1
	v_add3_u32 v16, v60, v16, s83
	v_bfe_u32 v248, v61, 16, 1
	v_lshrrev_b32_e32 v16, 16, v16
	v_add3_u32 v248, v61, v248, s83
	v_and_or_b32 v60, v248, s85, v16
	v_bfe_u32 v16, v62, 16, 1
	v_add3_u32 v16, v62, v16, s83
	v_bfe_u32 v248, v63, 16, 1
	v_lshrrev_b32_e32 v16, 16, v16
	v_add3_u32 v248, v63, v248, s83
	v_and_or_b32 v61, v248, s85, v16
	v_bfe_u32 v16, v80, 16, 1
	v_add3_u32 v16, v80, v16, s83
	v_bfe_u32 v248, v81, 16, 1
	v_lshrrev_b32_e32 v16, 16, v16
	v_add3_u32 v248, v81, v248, s83
	v_and_or_b32 v62, v248, s85, v16
	v_bfe_u32 v16, v82, 16, 1
	v_add3_u32 v16, v82, v16, s83
	v_bfe_u32 v248, v83, 16, 1
	v_lshrrev_b32_e32 v16, 16, v16
	v_add3_u32 v248, v83, v248, s83
	v_and_or_b32 v63, v248, s85, v16
	s_waitcnt vmcnt(12)
	v_bfe_u32 v16, v64, 16, 1
	v_add3_u32 v16, v64, v16, s83
	v_bfe_u32 v248, v65, 16, 1
	v_lshrrev_b32_e32 v16, 16, v16
	v_add3_u32 v248, v65, v248, s83
	v_and_or_b32 v64, v248, s85, v16
	v_bfe_u32 v16, v66, 16, 1
	v_add3_u32 v16, v66, v16, s83
	v_bfe_u32 v248, v67, 16, 1
	v_lshrrev_b32_e32 v16, 16, v16
	v_add3_u32 v248, v67, v248, s83
	v_and_or_b32 v65, v248, s85, v16
	v_bfe_u32 v16, v88, 16, 1
	v_add3_u32 v16, v88, v16, s83
	v_bfe_u32 v248, v89, 16, 1
	v_lshrrev_b32_e32 v16, 16, v16
	v_add3_u32 v248, v89, v248, s83
	v_and_or_b32 v66, v248, s85, v16
	v_bfe_u32 v16, v90, 16, 1
	v_add3_u32 v16, v90, v16, s83
	v_bfe_u32 v248, v91, 16, 1
	v_lshrrev_b32_e32 v16, 16, v16
	v_add3_u32 v248, v91, v248, s83
	v_and_or_b32 v67, v248, s85, v16
	s_waitcnt vmcnt(10)
	v_bfe_u32 v16, v68, 16, 1
	v_add3_u32 v16, v68, v16, s83
	v_bfe_u32 v248, v69, 16, 1
	v_lshrrev_b32_e32 v16, 16, v16
	v_add3_u32 v248, v69, v248, s83
	v_and_or_b32 v68, v248, s85, v16
	v_bfe_u32 v16, v70, 16, 1
	v_add3_u32 v16, v70, v16, s83
	v_bfe_u32 v248, v71, 16, 1
	v_lshrrev_b32_e32 v16, 16, v16
	v_add3_u32 v248, v71, v248, s83
	v_and_or_b32 v69, v248, s85, v16
	v_bfe_u32 v16, v96, 16, 1
	v_add3_u32 v16, v96, v16, s83
	v_bfe_u32 v248, v97, 16, 1
	v_lshrrev_b32_e32 v16, 16, v16
	v_add3_u32 v248, v97, v248, s83
	v_and_or_b32 v70, v248, s85, v16
	v_bfe_u32 v16, v98, 16, 1
	v_add3_u32 v16, v98, v16, s83
	v_bfe_u32 v248, v99, 16, 1
	v_lshrrev_b32_e32 v16, 16, v16
	v_add3_u32 v248, v99, v248, s83
	v_and_or_b32 v71, v248, s85, v16
	s_waitcnt vmcnt(8)
	v_bfe_u32 v16, v72, 16, 1
	v_add3_u32 v16, v72, v16, s83
	v_bfe_u32 v248, v73, 16, 1
	v_lshrrev_b32_e32 v16, 16, v16
	v_add3_u32 v248, v73, v248, s83
	v_and_or_b32 v72, v248, s85, v16
	v_bfe_u32 v16, v74, 16, 1
	v_add3_u32 v16, v74, v16, s83
	v_bfe_u32 v248, v75, 16, 1
	v_lshrrev_b32_e32 v16, 16, v16
	v_add3_u32 v248, v75, v248, s83
	v_and_or_b32 v73, v248, s85, v16
	v_bfe_u32 v16, v104, 16, 1
	v_add3_u32 v16, v104, v16, s83
	v_bfe_u32 v248, v105, 16, 1
	v_lshrrev_b32_e32 v16, 16, v16
	v_add3_u32 v248, v105, v248, s83
	v_and_or_b32 v74, v248, s85, v16
	v_bfe_u32 v16, v106, 16, 1
	v_add3_u32 v16, v106, v16, s83
	v_bfe_u32 v248, v107, 16, 1
	v_lshrrev_b32_e32 v16, 16, v16
	v_add3_u32 v248, v107, v248, s83
	v_and_or_b32 v75, v248, s85, v16
	s_waitcnt vmcnt(6)
	v_bfe_u32 v16, v76, 16, 1
	v_add3_u32 v16, v76, v16, s83
	v_bfe_u32 v248, v77, 16, 1
	v_lshrrev_b32_e32 v16, 16, v16
	v_add3_u32 v248, v77, v248, s83
	v_and_or_b32 v76, v248, s85, v16
	v_bfe_u32 v16, v78, 16, 1
	v_add3_u32 v16, v78, v16, s83
	v_bfe_u32 v248, v79, 16, 1
	v_lshrrev_b32_e32 v16, 16, v16
	v_add3_u32 v248, v79, v248, s83
	v_and_or_b32 v77, v248, s85, v16
	v_bfe_u32 v16, v112, 16, 1
	v_add3_u32 v16, v112, v16, s83
	v_bfe_u32 v248, v113, 16, 1
	v_lshrrev_b32_e32 v16, 16, v16
	v_add3_u32 v248, v113, v248, s83
	v_and_or_b32 v78, v248, s85, v16
	v_bfe_u32 v16, v114, 16, 1
	v_add3_u32 v16, v114, v16, s83
	v_bfe_u32 v248, v115, 16, 1
	v_lshrrev_b32_e32 v16, 16, v16
	v_add3_u32 v248, v115, v248, s83
	v_and_or_b32 v79, v248, s85, v16
	s_waitcnt vmcnt(4)
	v_bfe_u32 v16, v144, 16, 1
	v_add3_u32 v16, v144, v16, s83
	v_bfe_u32 v248, v145, 16, 1
	v_lshrrev_b32_e32 v16, 16, v16
	v_add3_u32 v248, v145, v248, s83
	v_and_or_b32 v144, v248, s85, v16
	v_bfe_u32 v16, v146, 16, 1
	v_add3_u32 v16, v146, v16, s83
	v_bfe_u32 v248, v147, 16, 1
	v_lshrrev_b32_e32 v16, 16, v16
	v_add3_u32 v248, v147, v248, s83
	v_and_or_b32 v145, v248, s85, v16
	v_bfe_u32 v16, v120, 16, 1
	v_add3_u32 v16, v120, v16, s83
	v_bfe_u32 v248, v121, 16, 1
	v_lshrrev_b32_e32 v16, 16, v16
	v_add3_u32 v248, v121, v248, s83
	v_and_or_b32 v146, v248, s85, v16
	v_bfe_u32 v16, v122, 16, 1
	v_add3_u32 v16, v122, v16, s83
	v_bfe_u32 v248, v123, 16, 1
	v_lshrrev_b32_e32 v16, 16, v16
	v_add3_u32 v248, v123, v248, s83
	v_and_or_b32 v147, v248, s85, v16
	s_waitcnt vmcnt(2)
	v_bfe_u32 v16, v148, 16, 1
	v_add3_u32 v16, v148, v16, s83
	v_bfe_u32 v248, v149, 16, 1
	v_lshrrev_b32_e32 v16, 16, v16
	v_add3_u32 v248, v149, v248, s83
	v_and_or_b32 v148, v248, s85, v16
	v_bfe_u32 v16, v150, 16, 1
	v_add3_u32 v16, v150, v16, s83
	v_bfe_u32 v248, v151, 16, 1
	v_lshrrev_b32_e32 v16, 16, v16
	v_add3_u32 v248, v151, v248, s83
	v_and_or_b32 v149, v248, s85, v16
	v_bfe_u32 v16, v128, 16, 1
	v_add3_u32 v16, v128, v16, s83
	v_bfe_u32 v248, v129, 16, 1
	v_lshrrev_b32_e32 v16, 16, v16
	v_add3_u32 v248, v129, v248, s83
	v_and_or_b32 v150, v248, s85, v16
	v_bfe_u32 v16, v130, 16, 1
	v_add3_u32 v16, v130, v16, s83
	v_bfe_u32 v248, v131, 16, 1
	v_lshrrev_b32_e32 v16, 16, v16
	v_add3_u32 v248, v131, v248, s83
	v_and_or_b32 v151, v248, s85, v16
	s_waitcnt vmcnt(0)
	v_bfe_u32 v16, v152, 16, 1
	v_add3_u32 v16, v152, v16, s83
	v_bfe_u32 v248, v153, 16, 1
	v_lshrrev_b32_e32 v16, 16, v16
	v_add3_u32 v248, v153, v248, s83
	v_and_or_b32 v152, v248, s85, v16
	v_bfe_u32 v16, v154, 16, 1
	v_add3_u32 v16, v154, v16, s83
	v_bfe_u32 v248, v155, 16, 1
	v_lshrrev_b32_e32 v16, 16, v16
	v_add3_u32 v248, v155, v248, s83
	v_and_or_b32 v153, v248, s85, v16
	v_bfe_u32 v16, v136, 16, 1
	v_add3_u32 v16, v136, v16, s83
	v_bfe_u32 v248, v137, 16, 1
	v_lshrrev_b32_e32 v16, 16, v16
	v_add3_u32 v248, v137, v248, s83
	v_and_or_b32 v154, v248, s85, v16
	v_bfe_u32 v16, v138, 16, 1
	v_add3_u32 v16, v138, v16, s83
	v_bfe_u32 v248, v139, 16, 1
	v_lshrrev_b32_e32 v16, 16, v16
	v_add3_u32 v248, v139, v248, s83
	v_and_or_b32 v155, v248, s85, v16
	s_nop 1
	v_mfma_f32_16x16x32_bf16 v[60:63], v[60:63], v[36:39], 0
	v_mfma_f32_16x16x32_bf16 v[60:63], v[64:67], v[40:43], v[60:63]
	v_mfma_f32_16x16x32_bf16 v[64:67], v[68:71], v[36:39], 0
	v_mfma_f32_16x16x32_bf16 v[64:67], v[72:75], v[40:43], v[64:67]
	v_mfma_f32_16x16x32_bf16 v[68:71], v[76:79], v[36:39], 0
	v_mfma_f32_16x16x32_bf16 v[72:75], v[148:151], v[36:39], 0
	v_cndmask_b32_e64 v84, 0, v190, s[8:9]
	v_lshlrev_b32_e32 v16, 2, v166
	v_ashrrev_i32_e32 v85, 31, v84
	v_lshl_add_u64 v[18:19], s[6:7], 0, v[16:17]
	v_lshlrev_b64 v[84:85], 10, v[84:85]
	v_cmp_gt_i32_e64 s[6:7], s38, v172
	v_lshl_add_u64 v[84:85], v[18:19], 0, v[84:85]
	v_lshl_add_u64 v[92:93], v[18:19], 0, v[92:93]
	v_lshl_add_u64 v[100:101], v[18:19], 0, v[100:101]
	v_lshl_add_u64 v[108:109], v[18:19], 0, v[108:109]
	v_lshl_add_u64 v[116:117], v[18:19], 0, v[116:117]
	v_lshl_add_u64 v[124:125], v[18:19], 0, v[124:125]
	v_lshl_add_u64 v[132:133], v[18:19], 0, v[132:133]
	v_cmp_gt_i32_e64 s[38:39], s38, v204
	v_cndmask_b32_e64 v80, 0, v172, s[6:7]
	global_load_dwordx4 v[88:91], v[84:85], off offset:512 nt
	global_load_dwordx4 v[96:99], v[92:93], off offset:512 nt
	v_cndmask_b32_e64 v84, 0, v191, s[10:11]
	v_cndmask_b32_e64 v92, 0, v193, s[14:15]
	global_load_dwordx4 v[104:107], v[100:101], off offset:512 nt
	global_load_dwordx4 v[112:115], v[108:109], off offset:512 nt
	v_cndmask_b32_e64 v100, 0, v195, s[18:19]
	v_cndmask_b32_e64 v108, 0, v197, s[22:23]
	global_load_dwordx4 v[120:123], v[116:117], off offset:512 nt
	global_load_dwordx4 v[128:131], v[124:125], off offset:512 nt
	v_cndmask_b32_e64 v116, 0, v199, s[26:27]
	v_cndmask_b32_e64 v124, 0, v201, s[30:31]
	global_load_dwordx4 v[136:139], v[132:133], off offset:512 nt
	v_cndmask_b32_e64 v132, 0, v203, s[36:37]
	v_cndmask_b32_e64 v140, 0, v204, s[38:39]
	v_ashrrev_i32_e32 v81, 31, v80
	v_ashrrev_i32_e32 v85, 31, v84
	v_ashrrev_i32_e32 v93, 31, v92
	v_ashrrev_i32_e32 v101, 31, v100
	v_ashrrev_i32_e32 v109, 31, v108
	v_ashrrev_i32_e32 v117, 31, v116
	v_ashrrev_i32_e32 v125, 31, v124
	v_ashrrev_i32_e32 v133, 31, v132
	v_ashrrev_i32_e32 v141, 31, v140
	v_lshlrev_b64 v[80:81], 10, v[80:81]
	v_lshlrev_b64 v[84:85], 10, v[84:85]
	v_lshlrev_b64 v[92:93], 10, v[92:93]
	v_lshlrev_b64 v[100:101], 10, v[100:101]
	v_lshlrev_b64 v[108:109], 10, v[108:109]
	v_lshlrev_b64 v[116:117], 10, v[116:117]
	v_lshlrev_b64 v[124:125], 10, v[124:125]
	v_lshlrev_b64 v[132:133], 10, v[132:133]
	v_lshlrev_b64 v[140:141], 10, v[140:141]
	v_lshl_add_u64 v[80:81], v[18:19], 0, v[80:81]
	v_lshl_add_u64 v[84:85], v[18:19], 0, v[84:85]
	v_lshl_add_u64 v[92:93], v[18:19], 0, v[92:93]
	v_lshl_add_u64 v[100:101], v[18:19], 0, v[100:101]
	v_lshl_add_u64 v[108:109], v[18:19], 0, v[108:109]
	v_lshl_add_u64 v[116:117], v[18:19], 0, v[116:117]
	v_lshl_add_u64 v[124:125], v[18:19], 0, v[124:125]
	v_lshl_add_u64 v[132:133], v[18:19], 0, v[132:133]
	v_lshl_add_u64 v[18:19], v[18:19], 0, v[140:141]
	global_load_dwordx4 v[80:83], v[80:81], off offset:512 nt
	v_mfma_f32_16x16x32_bf16 v[68:71], v[144:147], v[40:43], v[68:71]
	global_load_dwordx4 v[84:87], v[84:85], off offset:512 nt
	s_nop 0
	global_load_dwordx4 v[92:95], v[92:93], off offset:512 nt
	v_mfma_f32_16x16x32_bf16 v[72:75], v[152:155], v[40:43], v[72:75]
	global_load_dwordx4 v[100:103], v[100:101], off offset:512 nt
	s_nop 0
	global_load_dwordx4 v[108:111], v[108:109], off offset:512 nt
	s_nop 0
	global_load_dwordx4 v[116:119], v[116:117], off offset:512 nt
	s_nop 0
	global_load_dwordx4 v[124:127], v[124:125], off offset:512 nt
	s_nop 0
	global_load_dwordx4 v[132:135], v[132:133], off offset:512 nt
	s_nop 0
	global_load_dwordx4 v[140:143], v[18:19], off offset:512 nt
	v_add_u32_e32 v18, s46, v173
	v_add_u32_e32 v16, 1, v18
	v_add_u32_e32 v18, 0x200, v18
	v_cmp_lt_i32_e32 vcc, 0, v16
	v_cmp_gt_u32_e64 s[40:41], 63, v18
	s_or_b64 vcc, vcc, s[40:41]
	s_cbranch_vccz .LBB0_1475
	v_cmp_lt_i32_e32 vcc, v160, v16
	v_cmp_gt_i32_e64 s[40:41], v160, v18
	s_or_b64 vcc, vcc, s[40:41]
	v_cndmask_b32_e32 v154, v60, v246, vcc
	v_cmp_lt_i32_e32 vcc, v176, v16
	v_cmp_ge_i32_e64 s[40:41], v160, v18
	s_or_b64 vcc, vcc, s[40:41]
	v_cndmask_b32_e32 v153, v61, v246, vcc
	v_cmp_lt_i32_e32 vcc, v177, v16
	v_cmp_gt_i32_e64 s[40:41], v177, v18
	s_or_b64 vcc, vcc, s[40:41]
	v_cndmask_b32_e32 v152, v62, v246, vcc
	v_cmp_lt_i32_e32 vcc, v182, v16
	v_cmp_gt_i32_e64 s[40:41], v182, v18
	s_or_b64 vcc, vcc, s[40:41]
	v_cndmask_b32_e32 v151, v63, v246, vcc
	v_cmp_lt_i32_e32 vcc, v205, v16
	v_cmp_gt_i32_e64 s[40:41], v205, v18
	s_or_b64 vcc, vcc, s[40:41]
	v_cndmask_b32_e32 v150, v64, v246, vcc
	v_cmp_lt_i32_e32 vcc, v206, v16
	v_cmp_gt_i32_e64 s[40:41], v206, v18
	s_or_b64 vcc, vcc, s[40:41]
	v_cndmask_b32_e32 v149, v65, v246, vcc
	v_cmp_lt_i32_e32 vcc, v207, v16
	v_cmp_gt_i32_e64 s[40:41], v207, v18
	s_or_b64 vcc, vcc, s[40:41]
	v_cndmask_b32_e32 v148, v66, v246, vcc
	v_cmp_lt_i32_e32 vcc, v208, v16
	v_cmp_gt_i32_e64 s[40:41], v208, v18
	s_or_b64 vcc, vcc, s[40:41]
	v_cndmask_b32_e32 v147, v67, v246, vcc
	v_cmp_lt_i32_e32 vcc, v209, v16
	v_cmp_gt_i32_e64 s[40:41], v209, v18
	s_or_b64 vcc, vcc, s[40:41]
	v_cndmask_b32_e32 v146, v68, v246, vcc
	v_cmp_lt_i32_e32 vcc, v210, v16
	v_cmp_gt_i32_e64 s[40:41], v210, v18
	s_or_b64 vcc, vcc, s[40:41]
	v_cndmask_b32_e32 v145, v69, v246, vcc
	v_cmp_lt_i32_e32 vcc, v211, v16
	v_cmp_gt_i32_e64 s[40:41], v211, v18
	s_or_b64 vcc, vcc, s[40:41]
	v_cndmask_b32_e32 v144, v70, v246, vcc
	v_cmp_lt_i32_e32 vcc, v212, v16
	v_cmp_gt_i32_e64 s[40:41], v212, v18
	s_or_b64 vcc, vcc, s[40:41]
	v_cndmask_b32_e32 v79, v71, v246, vcc
	v_cmp_lt_i32_e32 vcc, v213, v16
	v_cmp_gt_i32_e64 s[40:41], v213, v18
	s_or_b64 vcc, vcc, s[40:41]
	v_max3_f32 v19, v154, s96, v153
	v_cndmask_b32_e32 v78, v72, v246, vcc
	v_cmp_lt_i32_e32 vcc, v214, v16
	v_cmp_gt_i32_e64 s[40:41], v214, v18
	v_max3_f32 v19, v19, v152, v151
	s_or_b64 vcc, vcc, s[40:41]
	v_max3_f32 v19, v19, v150, v149
	v_cndmask_b32_e32 v77, v73, v246, vcc
	v_cmp_lt_i32_e32 vcc, v215, v16
	v_cmp_gt_i32_e64 s[40:41], v215, v18
	v_max3_f32 v19, v19, v148, v147
	s_or_b64 vcc, vcc, s[40:41]
	v_max3_f32 v19, v19, v146, v145
	v_cndmask_b32_e32 v76, v74, v246, vcc
	v_cmp_lt_i32_e32 vcc, v216, v16
	v_cmp_gt_i32_e64 s[40:41], v216, v18
	v_max3_f32 v19, v19, v144, v79
	s_or_b64 vcc, vcc, s[40:41]
	v_max3_f32 v19, v19, v78, v77
	v_cndmask_b32_e32 v18, v75, v246, vcc
	v_max3_f32 v16, v19, v76, v18
	s_cbranch_execnz .LBB0_1470
	s_branch .LBB0_1469
